# S1/S3: redundant end-of-unit s_barrier removed (LDS regions written before the next unit's first barrier are disjoint from those still read after the last in-unit barrier), so fast waves start the nex
# speedup vs baseline: 1.0062x; 1.0061x over previous
; __device__ __forceinline__ const float* inp(const Params& p, int i) { asm volatile("" : "+s"(i)); return p.in[i]; }
; __device__ __forceinline__ unsigned cvt_pk_bf16(float lo, float hi) { f32x2 v = {lo, hi}; bf16x2v b = __builtin_convertvector(v, bf16x2v); return __builtin_bit_cast(unsigned, b); }
; __device__ void phase_s3(const Params& p, int layer, unsigned char* lds) {
;     ...
;             __syncthreads();
;             const float* nw = inp(p, 17) + (size_t)layer * 2048 + h * 64;
; #pragma unroll
;             for (int lti = 0; lti < 2; ++lti) {
;                 const int l = (2 * half + lti) * 16 + fr;
;                 const float scale = rsqrtf(((s_ssq[l] + s_ssq[64 + l]) + (s_ssq[128 + l] + s_ssq[192 + l])) * (1.f / 256.f) + EPS);
; #pragma unroll
;                 for (int pt = 0; pt < 4; ++pt) {
;                     const f32x4 w4 = *(const f32x4*)(nw + pt * 16 + fq * 4);
;                     const f32x4 o = acc1[lti][pt] * scale * w4;
;                     u32x2 w; w.x = cvt_pk_bf16(o[0], o[1]); w.y = cvt_pk_bf16(o[2], o[3]);
;                     *(u32x2*)(mix + pg8::img_off(row0 + l, 1024 + h * 64 + pt * 16 + fq * 4, D_MIX / 64)) = w;
;                 }
;             }
;         }
;         __syncthreads();
.LBB0_71:
	s_or_b64 exec, exec, s[4:5]
	s_load_dwordx2 s[4:5], s[0:1], 0x88
	s_waitcnt lgkmcnt(0)
	s_add_u32 s4, s4, s42
	s_addc_u32 s5, s5, s43
	v_lshlrev_b32_e32 v132, 2, v88
	v_lshl_add_u64 v[12:13], v[72:73], 2, s[4:5]
	v_lshl_add_u64 v[12:13], v[12:13], 0, v[132:133]
	global_load_dwordx4 v[108:111], v[12:13], off
	global_load_dwordx4 v[112:115], v[12:13], off offset:64
	global_load_dwordx4 v[116:119], v[12:13], off offset:128
	global_load_dwordx4 v[120:123], v[12:13], off offset:192
	s_barrier
	ds_read2st64_b32 v[16:17], v221 offset1:1
	ds_read2st64_b32 v[18:19], v221 offset0:2 offset1:3
	v_add_u32_e32 v14, 0x400, v72
	v_ashrrev_i32_e32 v14, 6, v14
	s_waitcnt lgkmcnt(0)
	v_mov_b32_e32 v24, v16
	v_mov_b32_e32 v25, v18
	v_mov_b32_e32 v18, v17
	v_pk_add_f32 v[32:33], v[24:25], v[18:19]
	s_ashr_i32 s4, s2, 5
	v_mad_u64_u32 v[14:15], s[4:5], s4, 48, v[14:15]
	v_lshlrev_b32_e32 v16, 6, v106
	v_ashrrev_i32_e32 v15, 31, v14
	v_readlane_b32 s4, v252, 21
	v_and_b32_e32 v18, 0x3c0, v16
	v_lshlrev_b32_e32 v16, 2, v106
	v_lshlrev_b64 v[14:15], 15, v[14:15]
	v_readlane_b32 s5, v252, 22
	v_and_b32_e32 v19, 32, v16
	v_lshlrev_b32_e32 v34, 7, v106
	v_lshl_add_u64 v[14:15], s[4:5], 0, v[14:15]
	v_and_b32_e32 v132, 0x4000, v34
	v_and_b32_e32 v42, 0x3000, v34
	v_or3_b32 v43, v18, v185, v19
	v_lshl_add_u64 v[16:17], v[14:15], 0, v[132:133]
	v_or_b32_e32 v132, v43, v42
	v_bitop3_b32 v48, v18, v19, v222 bitop3:0x36
	v_lshl_add_u64 v[34:35], v[16:17], 0, v[132:133]
	v_or_b32_e32 v132, v48, v42
	v_or_b32_e32 v42, 0x400, v42
	v_lshl_add_u64 v[40:41], v[16:17], 0, v[132:133]
	v_or_b32_e32 v132, v43, v42
	v_lshl_add_u64 v[18:19], v[16:17], 0, v[132:133]
	v_or_b32_e32 v132, v48, v42
	ds_read2st64_b32 v[42:43], v223 offset1:1
	ds_read2st64_b32 v[48:49], v223 offset0:2 offset1:3
	s_mov_b32 s4, 0x3b800000
	v_lshl_add_u64 v[16:17], v[16:17], 0, v[132:133]
	s_add_i32 s2, s2, s3
	s_waitcnt lgkmcnt(1)
	v_mov_b32_e32 v50, v42
	s_waitcnt lgkmcnt(0)
	v_mov_b32_e32 v51, v48
	v_mov_b32_e32 v48, v43
	v_pk_add_f32 v[42:43], v[50:51], v[48:49]
	v_mov_b32_e32 v49, v32
	v_mov_b32_e32 v48, v42
	v_mov_b32_e32 v32, v43
	v_pk_add_f32 v[32:33], v[48:49], v[32:33]
	s_cmpk_lt_i32 s2, 0x440
	v_pk_fma_f32 v[32:33], v[32:33], s[4:5], v[134:135] op_sel_hi:[1,0,0]
	s_nop 0
	v_mul_f32_e32 v42, 0x4b800000, v33
	v_cmp_gt_f32_e64 s[96:97], s14, v33
	v_cmp_gt_f32_e32 vcc, s14, v32
	s_nop 0
	v_cndmask_b32_e64 v33, v33, v42, s[96:97]
	v_rsq_f32_e32 v33, v33
	s_nop 0
	v_mul_f32_e32 v42, 0x45800000, v33
	v_cndmask_b32_e64 v42, v33, v42, s[96:97]
	v_pk_mul_f32 v[48:49], v[60:61], v[42:43] op_sel_hi:[1,0]
	v_pk_mul_f32 v[50:51], v[62:63], v[42:43] op_sel_hi:[1,0]
	s_waitcnt vmcnt(3)
	v_pk_mul_f32 v[24:25], v[108:109], v[48:49]
	v_pk_mul_f32 v[26:27], v[110:111], v[50:51]
	v_cvt_pk_bf16_f32 v24, v24, v25
	v_cvt_pk_bf16_f32 v25, v26, v27
	global_store_dwordx2 v[34:35], v[24:25], off
	v_pk_mul_f32 v[34:35], v[52:53], v[42:43] op_sel_hi:[1,0]
	v_pk_mul_f32 v[48:49], v[54:55], v[42:43] op_sel_hi:[1,0]
	s_waitcnt vmcnt(3)
	v_pk_mul_f32 v[24:25], v[112:113], v[34:35]
	v_pk_mul_f32 v[26:27], v[114:115], v[48:49]
	v_cvt_pk_bf16_f32 v24, v24, v25
	v_cvt_pk_bf16_f32 v25, v26, v27
	global_store_dwordx2 v[40:41], v[24:25], off
	v_pk_mul_f32 v[34:35], v[44:45], v[42:43] op_sel_hi:[1,0]
	v_pk_mul_f32 v[40:41], v[46:47], v[42:43] op_sel_hi:[1,0]
	s_waitcnt vmcnt(3)
	v_pk_mul_f32 v[24:25], v[116:117], v[34:35]
	v_pk_mul_f32 v[26:27], v[118:119], v[40:41]
	v_cvt_pk_bf16_f32 v24, v24, v25
	v_cvt_pk_bf16_f32 v25, v26, v27
	global_store_dwordx2 v[18:19], v[24:25], off
	v_pk_mul_f32 v[18:19], v[36:37], v[42:43] op_sel_hi:[1,0]
	v_pk_mul_f32 v[34:35], v[38:39], v[42:43] op_sel_hi:[1,0]
	s_waitcnt vmcnt(3)
	v_pk_mul_f32 v[18:19], v[120:121], v[18:19]
	v_pk_mul_f32 v[26:27], v[122:123], v[34:35]
	v_cvt_pk_bf16_f32 v18, v18, v19
	v_cvt_pk_bf16_f32 v19, v26, v27
	global_store_dwordx2 v[16:17], v[18:19], off
	v_mul_f32_e32 v16, 0x4b800000, v32
	v_cndmask_b32_e32 v16, v32, v16, vcc
	v_rsq_f32_e32 v16, v16
	s_nop 0
	v_mul_f32_e32 v17, 0x45800000, v16
	v_cndmask_b32_e32 v16, v16, v17, vcc
	v_or_b32_e32 v17, s21, v215
	v_lshlrev_b32_e32 v18, 6, v17
	v_and_b32_e32 v32, 0x3c0, v18
	v_lshlrev_b32_e32 v18, 2, v17
	v_lshlrev_b32_e32 v17, 7, v17
	v_and_b32_e32 v33, 32, v18
	v_pk_mul_f32 v[18:19], v[28:29], v[16:17] op_sel_hi:[1,0]
	v_pk_mul_f32 v[28:29], v[30:31], v[16:17] op_sel_hi:[1,0]
	v_and_b32_e32 v132, 0x4000, v17
	v_and_b32_e32 v17, 0x3800, v17
	v_lshl_add_u64 v[14:15], v[14:15], 0, v[132:133]
	v_pk_mul_f32 v[8:9], v[8:9], v[16:17] op_sel_hi:[1,0]
	v_pk_mul_f32 v[10:11], v[10:11], v[16:17] op_sel_hi:[1,0]
	v_pk_mul_f32 v[26:27], v[110:111], v[28:29]
	v_or3_b32 v28, v32, v185, v33
	v_pk_mul_f32 v[18:19], v[108:109], v[18:19]
	v_or_b32_e32 v132, v28, v17
	v_cvt_pk_bf16_f32 v18, v18, v19
	v_cvt_pk_bf16_f32 v19, v26, v27
	v_lshl_add_u64 v[24:25], v[14:15], 0, v[132:133]
	global_store_dwordx2 v[24:25], v[18:19], off
	v_pk_mul_f32 v[18:19], v[20:21], v[16:17] op_sel_hi:[1,0]
	v_pk_mul_f32 v[20:21], v[22:23], v[16:17] op_sel_hi:[1,0]
	v_bitop3_b32 v22, v32, v33, v222 bitop3:0x36
	v_or_b32_e32 v132, v22, v17
	v_or_b32_e32 v17, 0x400, v17
	v_pk_mul_f32 v[4:5], v[4:5], v[16:17] op_sel_hi:[1,0]
	v_pk_mul_f32 v[6:7], v[6:7], v[16:17] op_sel_hi:[1,0]
	v_pk_mul_f32 v[20:21], v[114:115], v[20:21]
	v_pk_mul_f32 v[18:19], v[112:113], v[18:19]
	s_nop 0
	v_cvt_pk_bf16_f32 v18, v18, v19
	v_cvt_pk_bf16_f32 v19, v20, v21
	v_lshl_add_u64 v[20:21], v[14:15], 0, v[132:133]
	global_store_dwordx2 v[20:21], v[18:19], off
	v_or_b32_e32 v132, v28, v17
	v_pk_mul_f32 v[10:11], v[118:119], v[10:11]
	v_pk_mul_f32 v[8:9], v[116:117], v[8:9]
	s_nop 0
	v_cvt_pk_bf16_f32 v8, v8, v9
	v_cvt_pk_bf16_f32 v9, v10, v11
	v_lshl_add_u64 v[10:11], v[14:15], 0, v[132:133]
	global_store_dwordx2 v[10:11], v[8:9], off
	v_or_b32_e32 v132, v22, v17
	v_pk_mul_f32 v[6:7], v[122:123], v[6:7]
	v_pk_mul_f32 v[4:5], v[120:121], v[4:5]
	s_nop 0
	v_cvt_pk_bf16_f32 v4, v4, v5
	v_cvt_pk_bf16_f32 v5, v6, v7
	v_lshl_add_u64 v[6:7], v[14:15], 0, v[132:133]
	global_store_dwordx2 v[6:7], v[4:5], off
	s_cbranch_scc0 .LBB0_180

; __device__ __forceinline__ unsigned cvt_pk_bf16(float lo, float hi) { f32x2 v = {lo, hi}; bf16x2v b = __builtin_convertvector(v, bf16x2v); return __builtin_bit_cast(unsigned, b); }
; __device__ void phase_s1(const Params& p, int layer, unsigned char* lds) {
;     ...
;         __syncthreads();
;         {
;             const int hh = wave >> 1, half = wave & 1, h = g * 4 + hh;
;             f32x4 acc[4][4];
; #pragma unroll
;             for (int a = 0; a < 4; ++a)
; #pragma unroll
;                 for (int b = 0; b < 4; ++b) acc[a][b] = (f32x4){0.f, 0.f, 0.f, 0.f};
; #pragma unroll
;             for (int ks = 0; ks < 2; ++ks) {
;                 bf16x8 af[4], bfr[4];
; #pragma unroll
;                 for (int a = 0; a < 4; ++a) af[a] = *(const bf16x8*)(s_BT + (half * 64 + a * 16 + fr) * 72 + ks * 32 + fq * 8);
; #pragma unroll
;                 for (int b = 0; b < 4; ++b) bfr[b] = *(const bf16x8*)(s_xwT + (hh * 64 + b * 16 + fr) * 72 + ks * 32 + fq * 8);
; #pragma unroll
;                 for (int a = 0; a < 4; ++a)
; #pragma unroll
;                     for (int b = 0; b < 4; ++b) acc[a][b] = __builtin_amdgcn_mfma_f32_16x16x32_bf16(af[a], bfr[b], acc[a][b], 0, 0, 0);
;             }
;             bf16_t* stp = ST + ((size_t)(c * 32 + h) * 64) * 128;
; #pragma unroll
;             for (int a = 0; a < 4; ++a)
; #pragma unroll
;                 for (int b = 0; b < 4; ++b) {
;                     u32x2 w; w.x = cvt_pk_bf16(acc[a][b][0], acc[a][b][1]); w.y = cvt_pk_bf16(acc[a][b][2], acc[a][b][3]);
;                     *(u32x2*)(stp + (size_t)(b * 16 + fr) * 128 + half * 64 + a * 16 + fq * 4) = w;
;                 }
;         }
;         __syncthreads();
;     }
.LBB0_328:
	s_or_b64 exec, exec, s[66:67]
	s_waitcnt lgkmcnt(0)
	s_barrier
	ds_read_b128 v[4:7], v138 offset:36864
	ds_read_b128 v[8:11], v138 offset:39168
	ds_read_b128 v[12:15], v138 offset:41472
	ds_read_b128 v[16:19], v138 offset:43776
	ds_read_b128 v[20:23], v139
	ds_read_b128 v[24:27], v139 offset:2304
	ds_read_b128 v[28:31], v139 offset:4608
	ds_read_b128 v[32:35], v139 offset:6912
	s_waitcnt lgkmcnt(3)
	v_mfma_f32_16x16x32_bf16 v[36:39], v[4:7], v[20:23], 0
	s_lshl_b32 s2, s2, 2
	s_lshl_b32 s4, s87, 5
	s_or_b32 s2, s4, s2
	s_waitcnt lgkmcnt(2)
	v_mfma_f32_16x16x32_bf16 v[40:43], v[4:7], v[24:27], 0
	v_mov_b32_e32 v93, v133
	v_mov_b32_e32 v95, v133
	v_mov_b32_e32 v97, v133
	s_waitcnt lgkmcnt(1)
	v_mfma_f32_16x16x32_bf16 v[44:47], v[4:7], v[28:31], 0
	v_mov_b32_e32 v99, v133
	s_mov_b64 s[4:5], 0x60
	s_add_i32 s86, s86, s3
	s_waitcnt lgkmcnt(0)
	v_mfma_f32_16x16x32_bf16 v[4:7], v[4:7], v[32:35], 0
	s_cmpk_lt_i32 s86, 0x440
	v_mfma_f32_16x16x32_bf16 v[48:51], v[8:11], v[20:23], 0
	v_mfma_f32_16x16x32_bf16 v[52:55], v[8:11], v[24:27], 0
	v_mfma_f32_16x16x32_bf16 v[56:59], v[8:11], v[28:31], 0
	v_mfma_f32_16x16x32_bf16 v[8:11], v[8:11], v[32:35], 0
	v_mfma_f32_16x16x32_bf16 v[60:63], v[12:15], v[20:23], 0
	v_mfma_f32_16x16x32_bf16 v[64:67], v[12:15], v[24:27], 0
	v_mfma_f32_16x16x32_bf16 v[68:71], v[12:15], v[28:31], 0
	v_mfma_f32_16x16x32_bf16 v[12:15], v[12:15], v[32:35], 0
	v_mfma_f32_16x16x32_bf16 v[72:75], v[16:19], v[20:23], 0
	v_mfma_f32_16x16x32_bf16 v[76:79], v[16:19], v[24:27], 0
	v_mfma_f32_16x16x32_bf16 v[28:31], v[16:19], v[28:31], 0
	v_mfma_f32_16x16x32_bf16 v[32:35], v[16:19], v[32:35], 0
	ds_read_b128 v[16:19], v138 offset:36928
	ds_read_b128 v[20:23], v138 offset:39232
	ds_read_b128 v[80:83], v138 offset:41536
	ds_read_b128 v[84:87], v138 offset:43840
	ds_read_b128 v[100:103], v139 offset:64
	ds_read_b128 v[104:107], v139 offset:2368
	ds_read_b128 v[140:143], v139 offset:4672
	ds_read_b128 v[144:147], v139 offset:6976
	s_waitcnt lgkmcnt(3)
	v_mfma_f32_16x16x32_bf16 v[36:39], v[16:19], v[100:103], v[36:39]
	s_waitcnt lgkmcnt(0)
	v_mfma_f32_16x16x32_bf16 v[152:155], v[20:23], v[144:147], v[8:11]
	v_mfma_f32_16x16x32_bf16 v[8:11], v[84:87], v[140:143], v[28:31]
	s_nop 2
	v_add_u32_e32 v28, s2, v121
	v_mfma_f32_16x16x32_bf16 v[40:43], v[16:19], v[104:107], v[40:43]
	v_ashrrev_i32_e32 v29, 31, v28
	v_lshlrev_b64 v[28:29], 14, v[28:29]
	v_lshl_add_u64 v[28:29], v[88:89], 0, v[28:29]
	v_mfma_f32_16x16x32_bf16 v[44:47], v[16:19], v[140:143], v[44:47]
	v_cvt_pk_bf16_f32 v30, v36, v37
	v_cvt_pk_bf16_f32 v31, v38, v39
	v_cvt_pk_bf16_f32 v8, v8, v9
	v_mfma_f32_16x16x32_bf16 v[148:151], v[16:19], v[144:147], v[4:7]
	v_cvt_pk_bf16_f32 v9, v10, v11
	v_mfma_f32_16x16x32_bf16 v[48:51], v[20:23], v[100:103], v[48:51]
	v_mfma_f32_16x16x32_bf16 v[4:7], v[84:87], v[144:147], v[32:35]
	s_nop 2
	v_lshl_add_u64 v[32:33], v[28:29], 0, v[92:93]
	v_mfma_f32_16x16x32_bf16 v[52:55], v[20:23], v[104:107], v[52:55]
	global_store_dwordx2 v[32:33], v[30:31], off
	v_cvt_pk_bf16_f32 v30, v40, v41
	v_cvt_pk_bf16_f32 v31, v42, v43
	v_lshl_add_u64 v[34:35], v[28:29], 0, v[94:95]
	v_mfma_f32_16x16x32_bf16 v[56:59], v[20:23], v[140:143], v[56:59]
	global_store_dwordx2 v[34:35], v[30:31], off
	v_cvt_pk_bf16_f32 v30, v44, v45
	v_cvt_pk_bf16_f32 v31, v46, v47
	v_lshl_add_u64 v[34:35], v[28:29], 0, v[96:97]
	global_store_dwordx2 v[34:35], v[30:31], off
	v_cvt_pk_bf16_f32 v30, v148, v149
	v_cvt_pk_bf16_f32 v31, v150, v151
	v_lshl_add_u64 v[34:35], v[28:29], 0, v[98:99]
	global_store_dwordx2 v[34:35], v[30:31], off
	v_lshl_add_u64 v[30:31], v[28:29], 0, 32
	v_cvt_pk_bf16_f32 v34, v48, v49
	v_cvt_pk_bf16_f32 v35, v50, v51
	v_mfma_f32_16x16x32_bf16 v[20:23], v[80:83], v[144:147], v[12:15]
	global_store_dwordx2 v[32:33], v[34:35], off offset:32
	v_cvt_pk_bf16_f32 v34, v52, v53
	v_cvt_pk_bf16_f32 v35, v54, v55
	v_lshl_add_u64 v[36:37], v[30:31], 0, v[94:95]
	v_mfma_f32_16x16x32_bf16 v[60:63], v[80:83], v[100:103], v[60:63]
	global_store_dwordx2 v[36:37], v[34:35], off
	v_cvt_pk_bf16_f32 v34, v56, v57
	v_cvt_pk_bf16_f32 v35, v58, v59
	v_lshl_add_u64 v[36:37], v[30:31], 0, v[96:97]
	v_mfma_f32_16x16x32_bf16 v[64:67], v[80:83], v[104:107], v[64:67]
	global_store_dwordx2 v[36:37], v[34:35], off
	v_cvt_pk_bf16_f32 v34, v152, v153
	v_cvt_pk_bf16_f32 v35, v154, v155
	v_mfma_f32_16x16x32_bf16 v[24:27], v[80:83], v[140:143], v[68:71]
	v_lshl_add_u64 v[30:31], v[30:31], 0, v[98:99]
	global_store_dwordx2 v[30:31], v[34:35], off
	v_lshl_add_u64 v[30:31], v[28:29], 0, 64
	v_mfma_f32_16x16x32_bf16 v[16:19], v[84:87], v[100:103], v[72:75]
	v_cvt_pk_bf16_f32 v20, v20, v21
	v_cvt_pk_bf16_f32 v21, v22, v23
	v_lshl_add_u64 v[22:23], v[30:31], 0, v[98:99]
	v_mfma_f32_16x16x32_bf16 v[12:15], v[84:87], v[104:107], v[76:79]
	v_cvt_pk_bf16_f32 v34, v60, v61
	v_cvt_pk_bf16_f32 v35, v62, v63
	global_store_dwordx2 v[22:23], v[20:21], off
	v_lshl_add_u64 v[20:21], v[28:29], 0, s[4:5]
	global_store_dwordx2 v[32:33], v[34:35], off offset:64
	v_cvt_pk_bf16_f32 v34, v64, v65
	v_cvt_pk_bf16_f32 v35, v66, v67
	v_lshl_add_u64 v[36:37], v[30:31], 0, v[94:95]
	v_cvt_pk_bf16_f32 v24, v24, v25
	v_cvt_pk_bf16_f32 v25, v26, v27
	v_lshl_add_u64 v[26:27], v[30:31], 0, v[96:97]
	v_cvt_pk_bf16_f32 v16, v16, v17
	v_cvt_pk_bf16_f32 v17, v18, v19
	v_cvt_pk_bf16_f32 v12, v12, v13
	v_cvt_pk_bf16_f32 v13, v14, v15
	v_lshl_add_u64 v[14:15], v[20:21], 0, v[94:95]
	v_lshl_add_u64 v[10:11], v[20:21], 0, v[96:97]
	v_cvt_pk_bf16_f32 v4, v4, v5
	v_cvt_pk_bf16_f32 v5, v6, v7
	v_lshl_add_u64 v[6:7], v[20:21], 0, v[98:99]
	global_store_dwordx2 v[36:37], v[34:35], off
	global_store_dwordx2 v[26:27], v[24:25], off
	global_store_dwordx2 v[32:33], v[16:17], off offset:96
	global_store_dwordx2 v[14:15], v[12:13], off
	global_store_dwordx2 v[10:11], v[8:9], off
	global_store_dwordx2 v[6:7], v[4:5], off
	s_cbranch_scc0 .LBB0_382
